# memory-attention (MODE 1) loop: K and V LDS fragment reads issued ahead with counted lgkmcnt waits, V reads as ds_read_b64 halves (same treatment as the diff-attention loop)
# baseline (speedup 1.0000x reference)
; #define MFMA16(a, b, c) __builtin_amdgcn_mfma_f32_16x16x32_bf16((a), (b), (c), 0, 0, 0)
; template <int MODE>
; __device__ __forceinline__ void attn_item(const Params& p, unsigned char* sm, int h, int tok0, int nrows, int kvt0, int ntiles, int nkeys, int qpos0, const int TIDX) {
;     ...
;         const unsigned char* Kb = sm + (t & 1) * 35840; const unsigned char* Vb = Kb + 17408;
;         f32x4 s[4];
; #pragma unroll
;         for (int kb = 0; kb < 4; ++kb) {
;             f32x4 acc = (f32x4){0.f, 0.f, 0.f, 0.f};
; #pragma unroll
;             for (int ks = 0; ks < KS; ++ks) {
;                 const bf16x8 A = *(const bf16x8*)(Kb + (16 * kb + r16) * 272 + (doff + 32 * ks + 8 * g) * 2);
;                 acc = MFMA16(A, Qf[ks], acc);
;             }
;             s[kb] = acc;
;         }
;     ...
;         for (int cb = 0; cb < 8; ++cb)
; #pragma unroll
;             for (int k2 = 0; k2 < 2; ++k2) {
;                 const u32x2 a0 = *(const u32x2*)(Vb + (16 * cb + r16) * 144 + (32 * k2 + 4 * g) * 2);
;                 const u32x2 a1 = *(const u32x2*)(Vb + (16 * cb + r16) * 144 + (32 * k2 + 16 + 4 * g) * 2);
;                 const bf16x8 A = __builtin_bit_cast(bf16x8, ((u32x4){a0.x, a0.y, a1.x, a1.y}));
;                 O[cb] = MFMA16(A, Pf[k2], O[cb]);
.LBB0_76:
	s_bitcmp1_b32 s14, 0
	s_cselect_b32 s14, 0x8c00, 0
	s_add_i32 s22, s14, 0
	v_add3_u32 v92, s22, v0, v111
	v_add3_u32 v244, s22, v82, v112
	ds_read_b128 v[120:123], v92
	ds_read_b128 v[124:127], v92 offset:64
	ds_read_b128 v[128:131], v92 offset:128
	ds_read_b128 v[132:135], v92 offset:192
	ds_read_b128 v[136:139], v92 offset:4352
	ds_read_b128 v[140:143], v92 offset:4416
	ds_read_b128 v[144:147], v92 offset:4480
	ds_read_b128 v[148:151], v92 offset:4544
	ds_read_b128 v[152:155], v92 offset:8704
	ds_read_b128 v[156:159], v92 offset:8768
	ds_read_b128 v[160:163], v92 offset:8832
	ds_read_b128 v[164:167], v92 offset:8896
	v_add_u32_e32 v245, 0x4000, v244
	ds_read_b64 v[220:221], v245 offset:1024
	ds_read_b64 v[222:223], v245 offset:1056
	s_add_i32 s21, s23, 64
	s_mov_b64 s[14:15], -1
	s_cmp_gt_i32 s21, s17
	s_waitcnt lgkmcnt(10)
	v_mfma_f32_16x16x32_bf16 v[66:69], v[120:123], v[2:5], 0
	v_mfma_f32_16x16x32_bf16 v[66:69], v[124:127], v[6:9], v[66:69]
	v_mfma_f32_16x16x32_bf16 v[66:69], v[128:131], v[10:13], v[66:69]
	v_mfma_f32_16x16x32_bf16 v[66:69], v[132:135], v[14:17], v[66:69]
	ds_read_b128 v[204:207], v92 offset:13056
	ds_read_b128 v[208:211], v92 offset:13120
	ds_read_b128 v[212:215], v92 offset:13184
	ds_read_b128 v[216:219], v92 offset:13248
	s_waitcnt lgkmcnt(10)
	v_mfma_f32_16x16x32_bf16 v[70:73], v[136:139], v[2:5], 0
	v_mfma_f32_16x16x32_bf16 v[70:73], v[140:143], v[6:9], v[70:73]
	v_mfma_f32_16x16x32_bf16 v[70:73], v[144:147], v[10:13], v[70:73]
	v_mfma_f32_16x16x32_bf16 v[70:73], v[148:151], v[14:17], v[70:73]
	v_add_u32_e32 v245, 0x4000, v244
	ds_read_b64 v[224:225], v245 offset:1088
	ds_read_b64 v[226:227], v245 offset:1120
	v_add_u32_e32 v245, 0x4800, v244
	ds_read_b64 v[228:229], v245 offset:1280
	ds_read_b64 v[230:231], v245 offset:1312
	s_waitcnt lgkmcnt(10)
	v_mfma_f32_16x16x32_bf16 v[74:77], v[152:155], v[2:5], 0
	v_mfma_f32_16x16x32_bf16 v[74:77], v[156:159], v[6:9], v[74:77]
	v_mfma_f32_16x16x32_bf16 v[74:77], v[160:163], v[10:13], v[74:77]
	v_mfma_f32_16x16x32_bf16 v[74:77], v[164:167], v[14:17], v[74:77]
	v_add_u32_e32 v245, 0x4800, v244
	ds_read_b64 v[232:233], v245 offset:1344
	ds_read_b64 v[234:235], v245 offset:1376
	v_add_u32_e32 v245, 0x5000, v244
	ds_read_b64 v[236:237], v245 offset:1536
	ds_read_b64 v[238:239], v245 offset:1568
	s_waitcnt lgkmcnt(8)
	v_mfma_f32_16x16x32_bf16 v[78:81], v[204:207], v[2:5], 0
	v_mfma_f32_16x16x32_bf16 v[78:81], v[208:211], v[6:9], v[78:81]
	v_mfma_f32_16x16x32_bf16 v[78:81], v[212:215], v[10:13], v[78:81]
	v_mfma_f32_16x16x32_bf16 v[78:81], v[216:219], v[14:17], v[78:81]
	v_add_u32_e32 v245, 0x5000, v244
	ds_read_b64 v[240:241], v245 offset:1600
	ds_read_b64 v[242:243], v245 offset:1632
	s_cbranch_scc1 .LBB0_78
	s_mov_b32 s24, 0x3e0293ee
	v_pk_fma_f32 v[90:91], v[66:67], s[24:25], 0 op_sel_hi:[1,0,0]
	s_mov_b32 s14, 0xf149f2ca
	v_max3_f32 v88, v90, s14, v91
	v_pk_fma_f32 v[92:93], v[68:69], s[24:25], 0 op_sel_hi:[1,0,0]
	s_mov_b64 s[14:15], 0
	v_max3_f32 v94, v88, v92, v93
	v_pk_fma_f32 v[88:89], v[70:71], s[24:25], 0 op_sel_hi:[1,0,0]
	s_nop 0
	v_max3_f32 v96, v94, v88, v89
	v_pk_fma_f32 v[94:95], v[72:73], s[24:25], 0 op_sel_hi:[1,0,0]
	s_nop 0
	v_max3_f32 v98, v96, v94, v95
	v_pk_fma_f32 v[96:97], v[74:75], s[24:25], 0 op_sel_hi:[1,0,0]
	s_nop 0
	v_max3_f32 v100, v98, v96, v97
	v_pk_fma_f32 v[98:99], v[76:77], s[24:25], 0 op_sel_hi:[1,0,0]
	s_nop 0
	v_max3_f32 v102, v100, v98, v99
	v_pk_fma_f32 v[100:101], v[78:79], s[24:25], 0 op_sel_hi:[1,0,0]
	s_nop 0
	v_max3_f32 v115, v102, v100, v101
	v_pk_fma_f32 v[102:103], v[80:81], s[24:25], 0 op_sel_hi:[1,0,0]
	s_nop 0
	v_max3_f32 v115, v115, v102, v103

; __device__ __forceinline__ unsigned pk2(float lo, float hi) { unsigned r; asm("v_cvt_pk_bf16_f32 %0, %1, %2" : "=v"(r) : "v"(lo), "v"(hi)); return r; }
; #define BAR_LDS() do { asm volatile("s_waitcnt lgkmcnt(0)" ::: "memory"); __builtin_amdgcn_s_barrier(); asm volatile("" ::: "memory"); } while (0)
; #define MFMA16(a, b, c) __builtin_amdgcn_mfma_f32_16x16x32_bf16((a), (b), (c), 0, 0, 0)
; #define AT_STORE(buf) do { unsigned char* b_ = sm + (buf) * 35840; _Pragma("unroll") for (int k_ = 0; k_ < 2; ++k_) { const int id_ = tid + 512 * k_; \
;         *(u32x4*)(b_ + (id_ >> 4) * 272 + (id_ & 15) * 16) = pkk[k_]; *(u32x4*)(b_ + 17408 + (id_ >> 3) * 144 + (id_ & 7) * 16) = pvv[k_]; } } while (0)
; template <int MODE>
; __device__ __forceinline__ void attn_item(const Params& p, unsigned char* sm, int h, int tok0, int nrows, int kvt0, int ntiles, int nkeys, int qpos0, const int TIDX) {
;     ...
;         mx = fmaxf(mx, __shfl_xor(mx, 16)); mx = fmaxf(mx, __shfl_xor(mx, 32));
;         const float mnew = fmaxf(m_run, mx), alpha = __builtin_amdgcn_exp2f(m_run - mnew); m_run = mnew;
;         float psum = 0.f;
; #pragma unroll
;         for (int kb = 0; kb < 4; ++kb)
; #pragma unroll
;             for (int j = 0; j < 4; ++j) { const float pv_ = __builtin_amdgcn_exp2f(s[kb][j] - mnew); s[kb][j] = pv_; psum += pv_; }
;         l_run = l_run * alpha + psum;
; #pragma unroll
;         for (int cb = 0; cb < 8; ++cb) O[cb] = O[cb] * alpha;
;         bf16x8 Pf[2];
; #pragma unroll
;         for (int k2 = 0; k2 < 2; ++k2) { u32x4 tt; tt.x = pk2(s[2 * k2][0], s[2 * k2][1]); tt.y = pk2(s[2 * k2][2], s[2 * k2][3]); tt.z = pk2(s[2 * k2 + 1][0], s[2 * k2 + 1][1]); tt.w = pk2(s[2 * k2 + 1][2], s[2 * k2 + 1][3]);
;             Pf[k2] = __builtin_bit_cast(bf16x8, tt); }
; #pragma unroll
;         for (int cb = 0; cb < 8; ++cb)
; #pragma unroll
;             for (int k2 = 0; k2 < 2; ++k2) {
;                 const u32x2 a0 = *(const u32x2*)(Vb + (16 * cb + r16) * 144 + (32 * k2 + 4 * g) * 2);
;                 const u32x2 a1 = *(const u32x2*)(Vb + (16 * cb + r16) * 144 + (32 * k2 + 16 + 4 * g) * 2);
;                 const bf16x8 A = __builtin_bit_cast(bf16x8, ((u32x4){a0.x, a0.y, a1.x, a1.y}));
;                 O[cb] = MFMA16(A, Pf[k2], O[cb]);
;             }
;         if (t + 1 < ntiles) AT_STORE((t + 1) & 1);
;         BAR_LDS();
.LBB0_80:
	ds_bpermute_b32 v66, v186, v115
	v_max_f32_e32 v67, v115, v115
	s_andn2_b64 vcc, exec, s[12:13]
	s_waitcnt lgkmcnt(0)
	v_max_f32_e32 v66, v66, v66
	v_max_f32_e32 v66, v67, v66
	ds_bpermute_b32 v67, v187, v66
	s_waitcnt lgkmcnt(0)
	v_max3_f32 v75, v114, v66, v67
	v_sub_f32_e32 v66, v114, v75
	v_exp_f32_e32 v74, v66
	v_sub_f32_e32 v66, v90, v75
	v_exp_f32_e32 v76, v66
	v_sub_f32_e32 v66, v91, v75
	v_exp_f32_e32 v77, v66
	v_sub_f32_e32 v66, v92, v75
	v_exp_f32_e32 v78, v66
	v_sub_f32_e32 v66, v93, v75
	v_exp_f32_e32 v79, v66
	v_sub_f32_e32 v66, v88, v75
	v_exp_f32_e32 v80, v66
	v_sub_f32_e32 v66, v89, v75
	v_exp_f32_e32 v81, v66
	v_sub_f32_e32 v66, v94, v75
	v_exp_f32_e32 v88, v66
	v_sub_f32_e32 v66, v95, v75
	v_exp_f32_e32 v89, v66
	v_sub_f32_e32 v66, v96, v75
	v_exp_f32_e32 v90, v66
	v_sub_f32_e32 v66, v97, v75
	v_exp_f32_e32 v91, v66
	v_sub_f32_e32 v66, v98, v75
	v_exp_f32_e32 v92, v66
	v_sub_f32_e32 v66, v99, v75
	v_exp_f32_e32 v93, v66
	v_sub_f32_e32 v66, v100, v75
	v_exp_f32_e32 v94, v66
	v_sub_f32_e32 v66, v101, v75
	v_exp_f32_e32 v95, v66
	v_sub_f32_e32 v66, v102, v75
	v_exp_f32_e32 v96, v66
	v_sub_f32_e32 v66, v103, v75
	v_pk_mul_f32 v[36:37], v[36:37], v[74:75] op_sel_hi:[1,0]
	v_pk_mul_f32 v[34:35], v[34:35], v[74:75] op_sel_hi:[1,0]
	v_cvt_pk_bf16_f32 v70, v76, v77
	v_cvt_pk_bf16_f32 v71, v78, v79
	v_cvt_pk_bf16_f32 v72, v80, v81
	v_cvt_pk_bf16_f32 v73, v88, v89
	v_exp_f32_e32 v97, v66
	s_nop 0
	v_mfma_f32_16x16x32_bf16 v[34:37], v[220:223], v[70:73], v[34:37]
	v_add_u32_e32 v245, 0x5800, v244
	ds_read_b64 v[220:221], v245 offset:1792
	ds_read_b64 v[222:223], v245 offset:1824
	v_pk_mul_f32 v[68:69], v[64:65], v[74:75] op_sel_hi:[1,0]
	v_pk_mul_f32 v[66:67], v[62:63], v[74:75] op_sel_hi:[1,0]
	v_cvt_pk_bf16_f32 v62, v90, v91
	v_cvt_pk_bf16_f32 v63, v92, v93
	v_cvt_pk_bf16_f32 v64, v94, v95
	v_cvt_pk_bf16_f32 v65, v96, v97
	v_pk_mul_f32 v[40:41], v[40:41], v[74:75] op_sel_hi:[1,0]
	s_nop 0
	v_mfma_f32_16x16x32_bf16 v[34:37], v[224:227], v[62:65], v[34:37]
	v_add_u32_e32 v245, 0x5800, v244
	ds_read_b64 v[224:225], v245 offset:1856
	ds_read_b64 v[226:227], v245 offset:1888
	v_pk_mul_f32 v[38:39], v[38:39], v[74:75] op_sel_hi:[1,0]
	v_pk_mul_f32 v[44:45], v[44:45], v[74:75] op_sel_hi:[1,0]
	v_pk_mul_f32 v[42:43], v[42:43], v[74:75] op_sel_hi:[1,0]
	v_mfma_f32_16x16x32_bf16 v[38:41], v[228:231], v[70:73], v[38:41]
	v_add_u32_e32 v245, 0x6800, v244
	ds_read_b64 v[228:229], v245 offset:0
	ds_read_b64 v[230:231], v245 offset:32
	v_pk_mul_f32 v[48:49], v[48:49], v[74:75] op_sel_hi:[1,0]
	v_mfma_f32_16x16x32_bf16 v[38:41], v[232:235], v[62:65], v[38:41]
	v_add_u32_e32 v245, 0x6800, v244
	ds_read_b64 v[232:233], v245 offset:64
	ds_read_b64 v[234:235], v245 offset:96
	v_pk_mul_f32 v[46:47], v[46:47], v[74:75] op_sel_hi:[1,0]
	v_pk_mul_f32 v[52:53], v[52:53], v[74:75] op_sel_hi:[1,0]
	v_mfma_f32_16x16x32_bf16 v[42:45], v[236:239], v[70:73], v[42:45]
	v_add_u32_e32 v245, 0x7000, v244
	ds_read_b64 v[236:237], v245 offset:256
	ds_read_b64 v[238:239], v245 offset:288
	v_pk_mul_f32 v[50:51], v[50:51], v[74:75] op_sel_hi:[1,0]
	v_mfma_f32_16x16x32_bf16 v[42:45], v[240:243], v[62:65], v[42:45]
	v_add_u32_e32 v245, 0x7000, v244
	ds_read_b64 v[240:241], v245 offset:320
	ds_read_b64 v[242:243], v245 offset:352
	v_pk_mul_f32 v[56:57], v[56:57], v[74:75] op_sel_hi:[1,0]
	v_pk_mul_f32 v[54:55], v[54:55], v[74:75] op_sel_hi:[1,0]
	s_waitcnt lgkmcnt(10)
	v_mfma_f32_16x16x32_bf16 v[46:49], v[220:223], v[70:73], v[46:49]
	v_add_u32_e32 v245, 0x7800, v244
	ds_read_b64 v[220:221], v245 offset:512
	ds_read_b64 v[222:223], v245 offset:544
	v_pk_mul_f32 v[60:61], v[60:61], v[74:75] op_sel_hi:[1,0]
	s_waitcnt lgkmcnt(10)
	v_mfma_f32_16x16x32_bf16 v[46:49], v[224:227], v[62:65], v[46:49]
	v_add_u32_e32 v245, 0x7800, v244
	ds_read_b64 v[224:225], v245 offset:576
	ds_read_b64 v[226:227], v245 offset:608
	v_pk_mul_f32 v[58:59], v[58:59], v[74:75] op_sel_hi:[1,0]
	s_waitcnt lgkmcnt(10)
	v_mfma_f32_16x16x32_bf16 v[50:53], v[228:231], v[70:73], v[50:53]
	v_add_u32_e32 v245, 0x8000, v244
	ds_read_b64 v[228:229], v245 offset:768
	ds_read_b64 v[230:231], v245 offset:800
	s_waitcnt lgkmcnt(10)
	v_mfma_f32_16x16x32_bf16 v[50:53], v[232:235], v[62:65], v[50:53]
	v_add_u32_e32 v245, 0x8000, v244
	ds_read_b64 v[232:233], v245 offset:832
	ds_read_b64 v[234:235], v245 offset:864
	s_waitcnt lgkmcnt(10)
	v_mfma_f32_16x16x32_bf16 v[54:57], v[236:239], v[70:73], v[54:57]
	s_waitcnt lgkmcnt(8)
	v_mfma_f32_16x16x32_bf16 v[54:57], v[240:243], v[62:65], v[54:57]
	s_waitcnt lgkmcnt(6)
	v_mfma_f32_16x16x32_bf16 v[58:61], v[220:223], v[70:73], v[58:61]
	s_waitcnt lgkmcnt(4)
	v_mfma_f32_16x16x32_bf16 v[58:61], v[224:227], v[62:65], v[58:61]
	s_waitcnt lgkmcnt(2)
	v_mfma_f32_16x16x32_bf16 v[66:69], v[228:231], v[70:73], v[66:69]
	s_waitcnt lgkmcnt(0)
	v_mfma_f32_16x16x32_bf16 v[62:65], v[232:235], v[62:65], v[66:69]
	s_cbranch_vccnz .LBB0_82
	s_bitcmp1_b32 s20, 0
	s_cselect_b32 s12, 0x8c00, 0
	s_add_i32 s12, s12, 0
	s_nop 0
	v_add_u32_e32 v66, s12, v104
	v_add_u32_e32 v67, v66, v106
	v_add_u32_e32 v68, s12, v105
	v_add_u32_e32 v69, v68, v107
	v_add_u32_e32 v66, v66, v108
	v_add_u32_e32 v68, v68, v109
	s_waitcnt vmcnt(3)
	ds_write_b128 v67, v[18:21]
	s_waitcnt vmcnt(2)
	ds_write_b128 v69, v[22:25] offset:17408
	s_waitcnt vmcnt(1)
	ds_write_b128 v66, v[26:29]
	s_waitcnt vmcnt(0)
	ds_write_b128 v68, v[30:33] offset:17408
